# wi 11/21 + P4 out-proj epilogue: second round of residual loads hoisted next to the first (free regs), single counted wait
# baseline (speedup 1.0000x reference)
.LBB0_743:
	v_lshl_add_u32 v132, s12, 8, v1
	v_ashrrev_i32_e32 v133, 31, v132
	s_lshl_b32 s12, s81, 8
	v_lshlrev_b64 v[132:133], 10, v[132:133]
	s_ashr_i32 s13, s12, 31
	v_lshl_add_u64 v[132:133], v[132:133], 0, s[12:13]
	v_lshl_add_u64 v[184:185], v[132:133], 1, v[174:175]
	global_load_dwordx4 v[150:153], v[184:185], off
	global_load_dwordx4 v[158:161], v[184:185], off offset:64
	v_mul_lo_u32 v130, v130, 12
	s_add_i32 s13, 0, 0x20000
	v_add_u32_e32 v191, s13, v130
	v_add_co_u32_e32 v130, vcc, 0x8000, v184
	v_lshrrev_b64 v[194:195], 6, v[132:133]
	s_nop 0
	v_addc_co_u32_e32 v131, vcc, 0, v185, vcc
	v_add_co_u32_e32 v132, vcc, 0x10000, v184
	ds_read2_b32 v[186:187], v191 offset0:1 offset1:2
	s_nop 0
	v_addc_co_u32_e32 v133, vcc, 0, v185, vcc
	global_load_dwordx4 v[142:145], v[130:131], off
	global_load_dwordx4 v[134:137], v[130:131], off offset:64
	v_add_co_u32_e32 v130, vcc, s86, v184
	global_load_dwordx4 v[154:157], v[132:133], off
	global_load_dwordx4 v[146:149], v[132:133], off offset:64
	v_addc_co_u32_e32 v131, vcc, 0, v185, vcc
	global_load_dwordx4 v[138:141], v[130:131], off
	s_nop 0
	global_load_dwordx4 v[130:133], v[130:131], off offset:64
	s_mov_b32 s13, 0
	s_mov_b32 s12, 0x40000
	v_lshl_add_u64 v[240:241], v[184:185], 0, s[12:13]
	global_load_dwordx4 v[204:207], v[240:241], off
	global_load_dwordx4 v[208:211], v[240:241], off offset:64
	s_mov_b32 s12, 0x48000
	v_lshl_add_u64 v[240:241], v[184:185], 0, s[12:13]
	global_load_dwordx4 v[212:215], v[240:241], off
	global_load_dwordx4 v[216:219], v[240:241], off offset:64
	s_mov_b32 s12, 0x50000
	v_lshl_add_u64 v[240:241], v[184:185], 0, s[12:13]
	global_load_dwordx4 v[220:223], v[240:241], off
	global_load_dwordx4 v[228:231], v[240:241], off offset:64
	s_mov_b32 s12, 0x58000
	v_lshl_add_u64 v[240:241], v[184:185], 0, s[12:13]
	global_load_dwordx4 v[232:235], v[240:241], off
	global_load_dwordx4 v[236:239], v[240:241], off offset:64
	s_lshl_b32 s12, s81, 2
	s_or_b32 s12, s12, s82
	v_and_b32_e32 v194, -16, v194
	s_ashr_i32 s13, s12, 31
	s_waitcnt vmcnt(8)
	v_lshlrev_b32_e32 v192, 16, v150
	v_and_b32_e32 v193, 0xffff0000, v150
	v_lshlrev_b32_e32 v150, 16, v151
	v_and_b32_e32 v151, 0xffff0000, v151
	v_lshlrev_b32_e32 v196, 16, v152
	v_and_b32_e32 v197, 0xffff0000, v152
	v_lshlrev_b32_e32 v152, 16, v153
	v_and_b32_e32 v153, 0xffff0000, v153
	s_waitcnt lgkmcnt(0)
	v_pk_mul_f32 v[192:193], v[186:187], v[192:193] op_sel:[1,0]
	v_pk_mul_f32 v[150:151], v[186:187], v[150:151] op_sel:[1,0]
	v_lshlrev_b32_e32 v198, 16, v158
	v_and_b32_e32 v199, 0xffff0000, v158
	v_lshlrev_b32_e32 v158, 16, v159
	v_and_b32_e32 v159, 0xffff0000, v159
	v_pk_mul_f32 v[196:197], v[186:187], v[196:197] op_sel:[1,0]
	v_pk_mul_f32 v[152:153], v[186:187], v[152:153] op_sel:[1,0]
	v_pk_fma_f32 v[32:33], v[32:33], v[186:187], v[150:151] op_sel_hi:[1,0,1]
	v_pk_fma_f32 v[30:31], v[30:31], v[186:187], v[192:193] op_sel_hi:[1,0,1]
	v_lshlrev_b32_e32 v200, 16, v160
	v_and_b32_e32 v201, 0xffff0000, v160
	v_lshlrev_b32_e32 v160, 16, v161
	v_and_b32_e32 v161, 0xffff0000, v161
	v_pk_mul_f32 v[198:199], v[186:187], v[198:199] op_sel:[1,0]
	v_pk_mul_f32 v[158:159], v[186:187], v[158:159] op_sel:[1,0]
	v_pk_fma_f32 v[28:29], v[28:29], v[186:187], v[152:153] op_sel_hi:[1,0,1]
	v_pk_fma_f32 v[26:27], v[26:27], v[186:187], v[196:197] op_sel_hi:[1,0,1]
	v_cvt_pk_bf16_f32 v150, v30, v31
	v_cvt_pk_bf16_f32 v151, v32, v33
	v_pk_fma_f32 v[30:31], v[30:31], v[30:31], 0 op_sel_hi:[1,1,0]
	v_pk_fma_f32 v[32:33], v[32:33], v[32:33], 0 op_sel_hi:[1,1,0]
	v_pk_mul_f32 v[200:201], v[186:187], v[200:201] op_sel:[1,0]
	v_pk_mul_f32 v[160:161], v[186:187], v[160:161] op_sel:[1,0]
	v_pk_fma_f32 v[52:53], v[52:53], v[186:187], v[158:159] op_sel_hi:[1,0,1]
	v_pk_fma_f32 v[50:51], v[50:51], v[186:187], v[198:199] op_sel_hi:[1,0,1]
	v_cvt_pk_bf16_f32 v152, v26, v27
	v_cvt_pk_bf16_f32 v153, v28, v29
	v_pk_fma_f32 v[28:29], v[28:29], v[28:29], v[32:33]
	v_pk_fma_f32 v[26:27], v[26:27], v[26:27], v[30:31]
	v_pk_fma_f32 v[44:45], v[44:45], v[186:187], v[160:161] op_sel_hi:[1,0,1]
	v_pk_fma_f32 v[42:43], v[42:43], v[186:187], v[200:201] op_sel_hi:[1,0,1]
	v_pk_fma_f32 v[26:27], v[50:51], v[50:51], v[26:27]
	v_pk_fma_f32 v[28:29], v[52:53], v[52:53], v[28:29]
	v_pk_fma_f32 v[26:27], v[42:43], v[42:43], v[26:27]
	v_pk_fma_f32 v[32:33], v[44:45], v[44:45], v[28:29]
	v_add_f32_e32 v26, v26, v27
	v_add_f32_e32 v27, v32, v33
	v_and_b32_e32 v32, 64, v190
	v_cvt_pk_bf16_f32 v158, v50, v51
	v_add_f32_e32 v26, v26, v27
	v_xor_b32_e32 v27, 16, v190
	v_add_u32_e32 v50, 64, v32
	v_cmp_lt_i32_e32 vcc, v27, v50
	v_mov_b32_dpp v192, v150 quad_perm:[1,0,3,2] row_mask:0xf bank_mask:0xf bound_ctrl:1
	v_cvt_pk_bf16_f32 v159, v52, v53
	v_cvt_pk_bf16_f32 v160, v42, v43
	v_cndmask_b32_e64 v42, v158, v192, s[4:5]
	v_cndmask_b32_e32 v27, v190, v27, vcc
	v_lshlrev_b32_e32 v192, 2, v27
	ds_bpermute_b32 v27, v192, v26
	v_cvt_pk_bf16_f32 v161, v44, v45
	v_mov_b32_dpp v30, v158 quad_perm:[1,0,3,2] row_mask:0xf bank_mask:0xf bound_ctrl:1
	v_mov_b32_dpp v31, v159 quad_perm:[1,0,3,2] row_mask:0xf bank_mask:0xf bound_ctrl:1
	v_mov_b32_dpp v186, v160 quad_perm:[1,0,3,2] row_mask:0xf bank_mask:0xf bound_ctrl:1
	s_waitcnt lgkmcnt(0)
	v_add_f32_e32 v26, v26, v27
	v_xor_b32_e32 v27, 32, v190
	v_cmp_lt_i32_e32 vcc, v27, v50
	v_mov_b32_dpp v187, v161 quad_perm:[1,0,3,2] row_mask:0xf bank_mask:0xf bound_ctrl:1
	v_lshl_add_u64 v[32:33], v[172:173], 1, v[184:185]
	v_cndmask_b32_e32 v27, v190, v27, vcc
	v_lshlrev_b32_e32 v193, 2, v27
	ds_bpermute_b32 v27, v193, v26
	v_mov_b32_dpp v43, v151 quad_perm:[1,0,3,2] row_mask:0xf bank_mask:0xf bound_ctrl:1
	v_mov_b32_dpp v44, v152 quad_perm:[1,0,3,2] row_mask:0xf bank_mask:0xf bound_ctrl:1
	v_mov_b32_dpp v45, v153 quad_perm:[1,0,3,2] row_mask:0xf bank_mask:0xf bound_ctrl:1
	v_cndmask_b32_e64 v28, v30, v150, s[4:5]
	v_cndmask_b32_e64 v29, v31, v151, s[4:5]
	v_cndmask_b32_e64 v30, v186, v152, s[4:5]
	v_cndmask_b32_e64 v31, v187, v153, s[4:5]
	v_lshl_add_u64 v[32:33], v[32:33], 0, v[170:171]
	v_lshl_add_u64 v[186:187], v[194:195], 2, s[10:11]
	v_cndmask_b32_e64 v43, v159, v43, s[4:5]
	v_cndmask_b32_e64 v44, v160, v44, s[4:5]
	v_cndmask_b32_e64 v45, v161, v45, s[4:5]
	global_store_dwordx4 v[32:33], v[28:31], off
	global_store_dwordx4 v[32:33], v[42:45], off offset:2048
	s_and_saveexec_b64 s[60:61], s[6:7]
	s_cbranch_execz .LBB0_745
	v_lshl_add_u64 v[28:29], s[12:13], 2, v[186:187]
	s_waitcnt lgkmcnt(0)
	v_add_f32_e32 v26, v26, v27
	global_store_dword v[28:29], v26, off

.LBB0_747:
	s_or_b64 exec, exec, s[60:61]
	v_mov_b32_e32 v2, s90
	s_nop 0
	ds_read_b128 v[86:89], v2
	ds_read_b128 v[66:69], v2
	ds_read_b128 v[14:17], v2
	s_waitcnt lgkmcnt(3)
	ds_read_b128 v[2:5], v2
	v_lshlrev_b32_e32 v198, 16, v154
	s_nop 0
	s_nop 0
	ds_read2_b32 v[196:197], v191 offset0:97 offset1:98
	v_and_b32_e32 v199, 0xffff0000, v154
	v_lshlrev_b32_e32 v154, 16, v155
	v_and_b32_e32 v155, 0xffff0000, v155
	v_lshl_add_u64 v[194:195], v[184:185], 0, s[20:21]
	s_waitcnt lgkmcnt(0)
	v_pk_mul_f32 v[154:155], v[196:197], v[154:155] op_sel:[1,0]
	v_pk_mul_f32 v[198:199], v[196:197], v[198:199] op_sel:[1,0]
	v_pk_fma_f32 v[96:97], v[96:97], v[196:197], v[154:155] op_sel_hi:[1,0,1]
	v_lshlrev_b32_e32 v154, 16, v156
	v_and_b32_e32 v155, 0xffff0000, v156
	v_lshlrev_b32_e32 v156, 16, v157
	v_and_b32_e32 v157, 0xffff0000, v157
	v_pk_fma_f32 v[94:95], v[94:95], v[196:197], v[198:199] op_sel_hi:[1,0,1]
	v_pk_mul_f32 v[154:155], v[196:197], v[154:155] op_sel:[1,0]
	v_pk_mul_f32 v[156:157], v[196:197], v[156:157] op_sel:[1,0]
	v_pk_fma_f32 v[82:83], v[82:83], v[196:197], v[154:155] op_sel_hi:[1,0,1]
	v_pk_fma_f32 v[84:85], v[84:85], v[196:197], v[156:157] op_sel_hi:[1,0,1]
	v_cvt_pk_bf16_f32 v154, v94, v95
	v_cvt_pk_bf16_f32 v155, v96, v97
	v_pk_fma_f32 v[94:95], v[94:95], v[94:95], 0 op_sel_hi:[1,1,0]
	v_pk_fma_f32 v[96:97], v[96:97], v[96:97], 0 op_sel_hi:[1,1,0]
	v_cvt_pk_bf16_f32 v156, v82, v83
	v_cvt_pk_bf16_f32 v157, v84, v85
	v_pk_fma_f32 v[82:83], v[82:83], v[82:83], v[94:95]
	v_pk_fma_f32 v[84:85], v[84:85], v[84:85], v[96:97]
	v_lshlrev_b32_e32 v94, 16, v146
	v_and_b32_e32 v95, 0xffff0000, v146
	v_lshlrev_b32_e32 v96, 16, v147
	v_and_b32_e32 v97, 0xffff0000, v147
	v_pk_mul_f32 v[94:95], v[196:197], v[94:95] op_sel:[1,0]
	v_pk_mul_f32 v[96:97], v[196:197], v[96:97] op_sel:[1,0]
	v_pk_fma_f32 v[22:23], v[22:23], v[196:197], v[94:95] op_sel_hi:[1,0,1]
	v_pk_fma_f32 v[24:25], v[24:25], v[196:197], v[96:97] op_sel_hi:[1,0,1]
	v_lshlrev_b32_e32 v94, 16, v148
	v_and_b32_e32 v95, 0xffff0000, v148
	v_lshlrev_b32_e32 v96, 16, v149
	v_and_b32_e32 v97, 0xffff0000, v149
	v_pk_mul_f32 v[94:95], v[196:197], v[94:95] op_sel:[1,0]
	v_pk_mul_f32 v[96:97], v[196:197], v[96:97] op_sel:[1,0]
	v_pk_fma_f32 v[10:11], v[10:11], v[196:197], v[94:95] op_sel_hi:[1,0,1]
	v_pk_fma_f32 v[12:13], v[12:13], v[196:197], v[96:97] op_sel_hi:[1,0,1]
	v_cvt_pk_bf16_f32 v94, v22, v23
	v_cvt_pk_bf16_f32 v95, v24, v25
	v_pk_fma_f32 v[22:23], v[22:23], v[22:23], v[82:83]
	v_pk_fma_f32 v[24:25], v[24:25], v[24:25], v[84:85]
	v_cvt_pk_bf16_f32 v96, v10, v11
	v_cvt_pk_bf16_f32 v97, v12, v13
	v_pk_fma_f32 v[10:11], v[10:11], v[10:11], v[22:23]
	v_pk_fma_f32 v[12:13], v[12:13], v[12:13], v[24:25]
	v_add_f32_e32 v10, v10, v11
	v_add_f32_e32 v11, v12, v13
	v_add_f32_e32 v10, v10, v11
	ds_bpermute_b32 v11, v192, v10
	v_mov_b32_dpp v22, v94 quad_perm:[1,0,3,2] row_mask:0xf bank_mask:0xf bound_ctrl:1
	v_mov_b32_dpp v23, v95 quad_perm:[1,0,3,2] row_mask:0xf bank_mask:0xf bound_ctrl:1
	v_mov_b32_dpp v24, v96 quad_perm:[1,0,3,2] row_mask:0xf bank_mask:0xf bound_ctrl:1
	v_mov_b32_dpp v25, v97 quad_perm:[1,0,3,2] row_mask:0xf bank_mask:0xf bound_ctrl:1
	s_waitcnt lgkmcnt(0)
	v_add_f32_e32 v10, v10, v11
	ds_bpermute_b32 v11, v193, v10
	v_lshl_add_u64 v[12:13], v[172:173], 1, v[194:195]
	v_mov_b32_dpp v82, v154 quad_perm:[1,0,3,2] row_mask:0xf bank_mask:0xf bound_ctrl:1
	v_mov_b32_dpp v83, v155 quad_perm:[1,0,3,2] row_mask:0xf bank_mask:0xf bound_ctrl:1
	v_mov_b32_dpp v84, v156 quad_perm:[1,0,3,2] row_mask:0xf bank_mask:0xf bound_ctrl:1
	v_mov_b32_dpp v85, v157 quad_perm:[1,0,3,2] row_mask:0xf bank_mask:0xf bound_ctrl:1
	v_cndmask_b32_e64 v22, v22, v154, s[4:5]
	v_cndmask_b32_e64 v23, v23, v155, s[4:5]
	v_cndmask_b32_e64 v24, v24, v156, s[4:5]
	v_cndmask_b32_e64 v25, v25, v157, s[4:5]
	v_lshl_add_u64 v[12:13], v[12:13], 0, v[170:171]
	v_cndmask_b32_e64 v82, v94, v82, s[4:5]
	v_cndmask_b32_e64 v83, v95, v83, s[4:5]
	v_cndmask_b32_e64 v84, v96, v84, s[4:5]
	v_cndmask_b32_e64 v85, v97, v85, s[4:5]
	global_store_dwordx4 v[12:13], v[22:25], off
	global_store_dwordx4 v[12:13], v[82:85], off offset:2048
	s_and_saveexec_b64 s[60:61], s[6:7]
	s_cbranch_execz .LBB0_749
	v_lshl_add_u64 v[12:13], s[12:13], 2, v[186:187]
	s_waitcnt lgkmcnt(0)
	v_add_f32_e32 v10, v10, v11
	global_store_dword v[12:13], v10, off offset:2048

.LBB0_751:
	s_or_b64 exec, exec, s[60:61]
	v_mov_b32_e32 v6, s90
	s_nop 0
	ds_read_b128 v[90:93], v6
	ds_read_b128 v[78:81], v6
	ds_read_b128 v[18:21], v6
	s_waitcnt lgkmcnt(3)
	ds_read_b128 v[6:9], v6
	v_add_u32_e32 v196, 0x604, v191
	s_nop 0
	s_nop 0
	ds_read2_b32 v[196:197], v196 offset1:1
	s_waitcnt vmcnt(8)
	v_lshlrev_b32_e32 v198, 16, v204
	v_and_b32_e32 v199, 0xffff0000, v204
	v_lshlrev_b32_e32 v204, 16, v205
	v_and_b32_e32 v205, 0xffff0000, v205
	s_waitcnt lgkmcnt(0)
	v_pk_mul_f32 v[204:205], v[196:197], v[204:205] op_sel:[1,0]
	v_pk_mul_f32 v[198:199], v[196:197], v[198:199] op_sel:[1,0]
	v_pk_fma_f32 v[120:121], v[120:121], v[196:197], v[204:205] op_sel_hi:[1,0,1]
	v_lshlrev_b32_e32 v204, 16, v206
	v_and_b32_e32 v205, 0xffff0000, v206
	v_lshlrev_b32_e32 v206, 16, v207
	v_and_b32_e32 v207, 0xffff0000, v207
	v_pk_fma_f32 v[118:119], v[118:119], v[196:197], v[198:199] op_sel_hi:[1,0,1]
	v_pk_mul_f32 v[204:205], v[196:197], v[204:205] op_sel:[1,0]
	v_pk_mul_f32 v[206:207], v[196:197], v[206:207] op_sel:[1,0]
	v_pk_fma_f32 v[102:103], v[102:103], v[196:197], v[204:205] op_sel_hi:[1,0,1]
	v_pk_fma_f32 v[104:105], v[104:105], v[196:197], v[206:207] op_sel_hi:[1,0,1]
	v_cvt_pk_bf16_f32 v204, v118, v119
	v_cvt_pk_bf16_f32 v205, v120, v121
	v_pk_fma_f32 v[118:119], v[118:119], v[118:119], 0 op_sel_hi:[1,1,0]
	v_pk_fma_f32 v[120:121], v[120:121], v[120:121], 0 op_sel_hi:[1,1,0]
	v_cvt_pk_bf16_f32 v206, v102, v103
	v_cvt_pk_bf16_f32 v207, v104, v105
	v_pk_fma_f32 v[102:103], v[102:103], v[102:103], v[118:119]
	v_pk_fma_f32 v[104:105], v[104:105], v[104:105], v[120:121]
	v_lshlrev_b32_e32 v118, 16, v208
	v_and_b32_e32 v119, 0xffff0000, v208
	v_lshlrev_b32_e32 v120, 16, v209
	v_and_b32_e32 v121, 0xffff0000, v209
	v_pk_mul_f32 v[118:119], v[196:197], v[118:119] op_sel:[1,0]
	v_pk_mul_f32 v[120:121], v[196:197], v[120:121] op_sel:[1,0]
	v_pk_fma_f32 v[62:63], v[62:63], v[196:197], v[118:119] op_sel_hi:[1,0,1]
	v_pk_fma_f32 v[64:65], v[64:65], v[196:197], v[120:121] op_sel_hi:[1,0,1]
	v_lshlrev_b32_e32 v118, 16, v210
	v_and_b32_e32 v119, 0xffff0000, v210
	v_lshlrev_b32_e32 v120, 16, v211
	v_and_b32_e32 v121, 0xffff0000, v211
	v_pk_mul_f32 v[118:119], v[196:197], v[118:119] op_sel:[1,0]
	v_pk_mul_f32 v[120:121], v[196:197], v[120:121] op_sel:[1,0]
	v_pk_fma_f32 v[38:39], v[38:39], v[196:197], v[118:119] op_sel_hi:[1,0,1]
	v_pk_fma_f32 v[40:41], v[40:41], v[196:197], v[120:121] op_sel_hi:[1,0,1]
	v_cvt_pk_bf16_f32 v118, v62, v63
	v_cvt_pk_bf16_f32 v119, v64, v65
	v_pk_fma_f32 v[62:63], v[62:63], v[62:63], v[102:103]
	v_pk_fma_f32 v[64:65], v[64:65], v[64:65], v[104:105]
	v_cvt_pk_bf16_f32 v120, v38, v39
	v_cvt_pk_bf16_f32 v121, v40, v41
	v_pk_fma_f32 v[38:39], v[38:39], v[38:39], v[62:63]
	v_pk_fma_f32 v[40:41], v[40:41], v[40:41], v[64:65]
	v_add_f32_e32 v38, v38, v39
	v_add_f32_e32 v39, v40, v41
	v_add_f32_e32 v38, v38, v39
	ds_bpermute_b32 v39, v192, v38
	v_lshl_add_u64 v[194:195], v[184:185], 0, s[26:27]
	v_mov_b32_dpp v62, v118 quad_perm:[1,0,3,2] row_mask:0xf bank_mask:0xf bound_ctrl:1
	v_mov_b32_dpp v63, v119 quad_perm:[1,0,3,2] row_mask:0xf bank_mask:0xf bound_ctrl:1
	v_mov_b32_dpp v64, v120 quad_perm:[1,0,3,2] row_mask:0xf bank_mask:0xf bound_ctrl:1
	s_waitcnt lgkmcnt(0)
	v_add_f32_e32 v38, v38, v39
	ds_bpermute_b32 v39, v193, v38
	v_mov_b32_dpp v65, v121 quad_perm:[1,0,3,2] row_mask:0xf bank_mask:0xf bound_ctrl:1
	v_lshl_add_u64 v[40:41], v[172:173], 1, v[194:195]
	v_mov_b32_dpp v102, v204 quad_perm:[1,0,3,2] row_mask:0xf bank_mask:0xf bound_ctrl:1
	v_mov_b32_dpp v103, v205 quad_perm:[1,0,3,2] row_mask:0xf bank_mask:0xf bound_ctrl:1
	v_mov_b32_dpp v104, v206 quad_perm:[1,0,3,2] row_mask:0xf bank_mask:0xf bound_ctrl:1
	v_mov_b32_dpp v105, v207 quad_perm:[1,0,3,2] row_mask:0xf bank_mask:0xf bound_ctrl:1
	v_cndmask_b32_e64 v62, v62, v204, s[4:5]
	v_cndmask_b32_e64 v63, v63, v205, s[4:5]
	v_cndmask_b32_e64 v64, v64, v206, s[4:5]
	v_cndmask_b32_e64 v65, v65, v207, s[4:5]
	v_lshl_add_u64 v[40:41], v[40:41], 0, v[170:171]
	v_cndmask_b32_e64 v102, v118, v102, s[4:5]
	v_cndmask_b32_e64 v103, v119, v103, s[4:5]
	v_cndmask_b32_e64 v104, v120, v104, s[4:5]
	v_cndmask_b32_e64 v105, v121, v105, s[4:5]
	global_store_dwordx4 v[40:41], v[62:65], off
	global_store_dwordx4 v[40:41], v[102:105], off offset:2048
	s_and_saveexec_b64 s[60:61], s[6:7]
	s_cbranch_execz .LBB0_753
	v_lshl_add_u64 v[40:41], s[12:13], 2, v[186:187]
	s_waitcnt lgkmcnt(0)
	v_add_f32_e32 v62, v38, v39
	v_add_co_u32_e32 v38, vcc, 0x2000, v40
	s_nop 1
	v_addc_co_u32_e32 v39, vcc, 0, v41, vcc
	global_store_dword v[38:39], v62, off
.LBB0_753:
	s_or_b64 exec, exec, s[60:61]
	v_mov_b32_e32 v38, s90
	v_add_u32_e32 v210, 0x6c4, v191
	ds_read_b128 v[118:121], v38
	ds_read_b128 v[102:105], v38
	ds_read_b128 v[62:65], v38
	s_waitcnt lgkmcnt(3)
	ds_read_b128 v[38:41], v38
	ds_read2_b32 v[210:211], v210 offset1:1
	v_lshlrev_b32_e32 v204, 16, v212
	v_and_b32_e32 v205, 0xffff0000, v212
	v_lshlrev_b32_e32 v212, 16, v213
	v_and_b32_e32 v213, 0xffff0000, v213
	s_waitcnt lgkmcnt(0)
	v_pk_mul_f32 v[212:213], v[210:211], v[212:213] op_sel:[1,0]
	v_pk_mul_f32 v[204:205], v[210:211], v[204:205] op_sel:[1,0]
	v_pk_fma_f32 v[116:117], v[116:117], v[210:211], v[212:213] op_sel_hi:[1,0,1]
	v_lshlrev_b32_e32 v212, 16, v214
	v_and_b32_e32 v213, 0xffff0000, v214
	v_lshlrev_b32_e32 v214, 16, v215
	v_and_b32_e32 v215, 0xffff0000, v215
	v_pk_fma_f32 v[114:115], v[114:115], v[210:211], v[204:205] op_sel_hi:[1,0,1]
	v_pk_mul_f32 v[212:213], v[210:211], v[212:213] op_sel:[1,0]
	v_pk_mul_f32 v[214:215], v[210:211], v[214:215] op_sel:[1,0]
	v_pk_fma_f32 v[98:99], v[98:99], v[210:211], v[212:213] op_sel_hi:[1,0,1]
	v_pk_fma_f32 v[100:101], v[100:101], v[210:211], v[214:215] op_sel_hi:[1,0,1]
	v_cvt_pk_bf16_f32 v212, v114, v115
	v_cvt_pk_bf16_f32 v213, v116, v117
	v_pk_fma_f32 v[114:115], v[114:115], v[114:115], 0 op_sel_hi:[1,1,0]
	v_pk_fma_f32 v[116:117], v[116:117], v[116:117], 0 op_sel_hi:[1,1,0]
	v_cvt_pk_bf16_f32 v214, v98, v99
	v_cvt_pk_bf16_f32 v215, v100, v101
	v_pk_fma_f32 v[98:99], v[98:99], v[98:99], v[114:115]
	v_pk_fma_f32 v[100:101], v[100:101], v[100:101], v[116:117]
	v_lshlrev_b32_e32 v114, 16, v216
	v_and_b32_e32 v115, 0xffff0000, v216
	v_lshlrev_b32_e32 v116, 16, v217
	v_and_b32_e32 v117, 0xffff0000, v217
	v_pk_mul_f32 v[114:115], v[210:211], v[114:115] op_sel:[1,0]
	v_pk_mul_f32 v[116:117], v[210:211], v[116:117] op_sel:[1,0]
	v_pk_fma_f32 v[58:59], v[58:59], v[210:211], v[114:115] op_sel_hi:[1,0,1]
	v_pk_fma_f32 v[60:61], v[60:61], v[210:211], v[116:117] op_sel_hi:[1,0,1]
	v_lshlrev_b32_e32 v114, 16, v218
	v_and_b32_e32 v115, 0xffff0000, v218
	v_lshlrev_b32_e32 v116, 16, v219
	v_and_b32_e32 v117, 0xffff0000, v219
	v_pk_mul_f32 v[114:115], v[210:211], v[114:115] op_sel:[1,0]
	v_pk_mul_f32 v[116:117], v[210:211], v[116:117] op_sel:[1,0]
	v_pk_fma_f32 v[34:35], v[34:35], v[210:211], v[114:115] op_sel_hi:[1,0,1]
	v_pk_fma_f32 v[36:37], v[36:37], v[210:211], v[116:117] op_sel_hi:[1,0,1]
	v_cvt_pk_bf16_f32 v114, v58, v59
	v_cvt_pk_bf16_f32 v115, v60, v61
	v_pk_fma_f32 v[58:59], v[58:59], v[58:59], v[98:99]
	v_pk_fma_f32 v[60:61], v[60:61], v[60:61], v[100:101]
	v_cvt_pk_bf16_f32 v116, v34, v35
	v_cvt_pk_bf16_f32 v117, v36, v37
	v_pk_fma_f32 v[34:35], v[34:35], v[34:35], v[58:59]
	v_pk_fma_f32 v[36:37], v[36:37], v[36:37], v[60:61]
	v_add_f32_e32 v34, v34, v35
	v_add_f32_e32 v35, v36, v37
	v_add_f32_e32 v34, v34, v35
	ds_bpermute_b32 v35, v192, v34
	v_lshl_add_u64 v[208:209], v[184:185], 0, s[28:29]
	v_mov_b32_dpp v58, v114 quad_perm:[1,0,3,2] row_mask:0xf bank_mask:0xf bound_ctrl:1
	v_mov_b32_dpp v59, v115 quad_perm:[1,0,3,2] row_mask:0xf bank_mask:0xf bound_ctrl:1
	v_mov_b32_dpp v60, v116 quad_perm:[1,0,3,2] row_mask:0xf bank_mask:0xf bound_ctrl:1
	s_waitcnt lgkmcnt(0)
	v_add_f32_e32 v34, v34, v35
	ds_bpermute_b32 v35, v193, v34
	v_mov_b32_dpp v61, v117 quad_perm:[1,0,3,2] row_mask:0xf bank_mask:0xf bound_ctrl:1
	v_lshl_add_u64 v[36:37], v[172:173], 1, v[208:209]
	v_mov_b32_dpp v98, v212 quad_perm:[1,0,3,2] row_mask:0xf bank_mask:0xf bound_ctrl:1
	v_mov_b32_dpp v99, v213 quad_perm:[1,0,3,2] row_mask:0xf bank_mask:0xf bound_ctrl:1
	v_mov_b32_dpp v100, v214 quad_perm:[1,0,3,2] row_mask:0xf bank_mask:0xf bound_ctrl:1
	v_mov_b32_dpp v101, v215 quad_perm:[1,0,3,2] row_mask:0xf bank_mask:0xf bound_ctrl:1
	v_cndmask_b32_e64 v58, v58, v212, s[4:5]
	v_cndmask_b32_e64 v59, v59, v213, s[4:5]
	v_cndmask_b32_e64 v60, v60, v214, s[4:5]
	v_cndmask_b32_e64 v61, v61, v215, s[4:5]
	v_lshl_add_u64 v[36:37], v[36:37], 0, v[170:171]
	v_cndmask_b32_e64 v98, v114, v98, s[4:5]
	v_cndmask_b32_e64 v99, v115, v99, s[4:5]
	v_cndmask_b32_e64 v100, v116, v100, s[4:5]
	v_cndmask_b32_e64 v101, v117, v101, s[4:5]
	global_store_dwordx4 v[36:37], v[58:61], off
	global_store_dwordx4 v[36:37], v[98:101], off offset:2048
	s_and_saveexec_b64 s[60:61], s[6:7]
	s_cbranch_execz .LBB0_755
	v_lshl_add_u64 v[36:37], s[12:13], 2, v[186:187]
	s_waitcnt lgkmcnt(0)
	v_add_f32_e32 v58, v34, v35
	v_add_co_u32_e32 v34, vcc, 0x2000, v36
	s_nop 1
	v_addc_co_u32_e32 v35, vcc, 0, v37, vcc
	global_store_dword v[34:35], v58, off offset:1024
.LBB0_755:
	s_or_b64 exec, exec, s[60:61]
	v_mov_b32_e32 v34, s90
	v_add_u32_e32 v218, 0x784, v191
	ds_read_b128 v[114:117], v34
	ds_read_b128 v[98:101], v34
	ds_read_b128 v[58:61], v34
	s_waitcnt lgkmcnt(3)
	ds_read_b128 v[34:37], v34
	ds_read2_b32 v[218:219], v218 offset1:1
	v_lshlrev_b32_e32 v212, 16, v220
	v_and_b32_e32 v213, 0xffff0000, v220
	v_lshlrev_b32_e32 v214, 16, v221
	v_and_b32_e32 v215, 0xffff0000, v221
	s_waitcnt lgkmcnt(0)
	v_pk_mul_f32 v[212:213], v[218:219], v[212:213] op_sel:[1,0]
	v_pk_mul_f32 v[214:215], v[218:219], v[214:215] op_sel:[1,0]
	v_pk_fma_f32 v[126:127], v[126:127], v[218:219], v[212:213] op_sel_hi:[1,0,1]
	v_pk_fma_f32 v[128:129], v[128:129], v[218:219], v[214:215] op_sel_hi:[1,0,1]
	v_lshlrev_b32_e32 v212, 16, v222
	v_and_b32_e32 v213, 0xffff0000, v222
	v_lshlrev_b32_e32 v214, 16, v223
	v_and_b32_e32 v215, 0xffff0000, v223
	v_pk_mul_f32 v[212:213], v[218:219], v[212:213] op_sel:[1,0]
	v_pk_mul_f32 v[214:215], v[218:219], v[214:215] op_sel:[1,0]
	v_pk_fma_f32 v[110:111], v[110:111], v[218:219], v[212:213] op_sel_hi:[1,0,1]
	v_pk_fma_f32 v[112:113], v[112:113], v[218:219], v[214:215] op_sel_hi:[1,0,1]
	v_cvt_pk_bf16_f32 v212, v126, v127
	v_cvt_pk_bf16_f32 v213, v128, v129
	v_pk_fma_f32 v[126:127], v[126:127], v[126:127], 0 op_sel_hi:[1,1,0]
	v_pk_fma_f32 v[128:129], v[128:129], v[128:129], 0 op_sel_hi:[1,1,0]
	v_cvt_pk_bf16_f32 v214, v110, v111
	v_cvt_pk_bf16_f32 v215, v112, v113
	v_pk_fma_f32 v[110:111], v[110:111], v[110:111], v[126:127]
	v_pk_fma_f32 v[112:113], v[112:113], v[112:113], v[128:129]
	v_lshlrev_b32_e32 v126, 16, v228
	v_and_b32_e32 v127, 0xffff0000, v228
	v_lshlrev_b32_e32 v128, 16, v229
	v_and_b32_e32 v129, 0xffff0000, v229
	v_pk_mul_f32 v[126:127], v[218:219], v[126:127] op_sel:[1,0]
	v_pk_mul_f32 v[128:129], v[218:219], v[128:129] op_sel:[1,0]
	v_pk_fma_f32 v[74:75], v[74:75], v[218:219], v[126:127] op_sel_hi:[1,0,1]
	v_pk_fma_f32 v[76:77], v[76:77], v[218:219], v[128:129] op_sel_hi:[1,0,1]
	v_lshlrev_b32_e32 v126, 16, v230
	v_and_b32_e32 v127, 0xffff0000, v230
	v_lshlrev_b32_e32 v128, 16, v231
	v_and_b32_e32 v129, 0xffff0000, v231
	v_pk_mul_f32 v[126:127], v[218:219], v[126:127] op_sel:[1,0]
	v_pk_mul_f32 v[128:129], v[218:219], v[128:129] op_sel:[1,0]
	v_pk_fma_f32 v[54:55], v[54:55], v[218:219], v[126:127] op_sel_hi:[1,0,1]
	v_pk_fma_f32 v[56:57], v[56:57], v[218:219], v[128:129] op_sel_hi:[1,0,1]
	v_cvt_pk_bf16_f32 v126, v74, v75
	v_cvt_pk_bf16_f32 v127, v76, v77
	v_pk_fma_f32 v[74:75], v[74:75], v[74:75], v[110:111]
	v_pk_fma_f32 v[76:77], v[76:77], v[76:77], v[112:113]
	v_cvt_pk_bf16_f32 v128, v54, v55
	v_cvt_pk_bf16_f32 v129, v56, v57
	v_pk_fma_f32 v[54:55], v[54:55], v[54:55], v[74:75]
	v_pk_fma_f32 v[56:57], v[56:57], v[56:57], v[76:77]
	v_add_f32_e32 v54, v54, v55
	v_add_f32_e32 v55, v56, v57
	v_add_f32_e32 v54, v54, v55
	ds_bpermute_b32 v55, v192, v54
	v_lshl_add_u64 v[216:217], v[184:185], 0, s[30:31]
	v_mov_b32_dpp v74, v126 quad_perm:[1,0,3,2] row_mask:0xf bank_mask:0xf bound_ctrl:1
	v_mov_b32_dpp v75, v127 quad_perm:[1,0,3,2] row_mask:0xf bank_mask:0xf bound_ctrl:1
	v_mov_b32_dpp v76, v128 quad_perm:[1,0,3,2] row_mask:0xf bank_mask:0xf bound_ctrl:1
	s_waitcnt lgkmcnt(0)
	v_add_f32_e32 v54, v54, v55
	ds_bpermute_b32 v55, v193, v54
	v_mov_b32_dpp v77, v129 quad_perm:[1,0,3,2] row_mask:0xf bank_mask:0xf bound_ctrl:1
	v_lshl_add_u64 v[56:57], v[172:173], 1, v[216:217]
	v_mov_b32_dpp v110, v212 quad_perm:[1,0,3,2] row_mask:0xf bank_mask:0xf bound_ctrl:1
	v_mov_b32_dpp v111, v213 quad_perm:[1,0,3,2] row_mask:0xf bank_mask:0xf bound_ctrl:1
	v_mov_b32_dpp v112, v214 quad_perm:[1,0,3,2] row_mask:0xf bank_mask:0xf bound_ctrl:1
	v_mov_b32_dpp v113, v215 quad_perm:[1,0,3,2] row_mask:0xf bank_mask:0xf bound_ctrl:1
	v_cndmask_b32_e64 v74, v74, v212, s[4:5]
	v_cndmask_b32_e64 v75, v75, v213, s[4:5]
	v_cndmask_b32_e64 v76, v76, v214, s[4:5]
	v_cndmask_b32_e64 v77, v77, v215, s[4:5]
	v_lshl_add_u64 v[56:57], v[56:57], 0, v[170:171]
	v_cndmask_b32_e64 v110, v126, v110, s[4:5]
	v_cndmask_b32_e64 v111, v127, v111, s[4:5]
	v_cndmask_b32_e64 v112, v128, v112, s[4:5]
	v_cndmask_b32_e64 v113, v129, v113, s[4:5]
	global_store_dwordx4 v[56:57], v[74:77], off
	global_store_dwordx4 v[56:57], v[110:113], off offset:2048
	s_and_saveexec_b64 s[60:61], s[6:7]
	s_cbranch_execz .LBB0_757
	v_lshl_add_u64 v[56:57], s[12:13], 2, v[186:187]
	s_waitcnt lgkmcnt(0)
	v_add_f32_e32 v74, v54, v55
	v_add_co_u32_e32 v54, vcc, 0x2000, v56
	s_nop 1
	v_addc_co_u32_e32 v55, vcc, 0, v57, vcc
	global_store_dword v[54:55], v74, off offset:2048
.LBB0_757:
	s_or_b64 exec, exec, s[60:61]
	v_mov_b32_e32 v54, s90
	v_add_u32_e32 v218, 0x844, v191
	ds_read_b128 v[126:129], v54
	ds_read_b128 v[110:113], v54
	ds_read_b128 v[74:77], v54
	s_waitcnt lgkmcnt(3)
	ds_read_b128 v[54:57], v54
	ds_read2_b32 v[218:219], v218 offset1:1
	v_lshlrev_b32_e32 v212, 16, v232
	v_and_b32_e32 v213, 0xffff0000, v232
	v_lshlrev_b32_e32 v232, 16, v233
	v_and_b32_e32 v233, 0xffff0000, v233
	s_waitcnt lgkmcnt(0)
	v_pk_mul_f32 v[232:233], v[218:219], v[232:233] op_sel:[1,0]
	v_pk_mul_f32 v[212:213], v[218:219], v[212:213] op_sel:[1,0]
	v_pk_fma_f32 v[124:125], v[124:125], v[218:219], v[232:233] op_sel_hi:[1,0,1]
	v_lshlrev_b32_e32 v232, 16, v234
	v_and_b32_e32 v233, 0xffff0000, v234
	v_lshlrev_b32_e32 v234, 16, v235
	v_and_b32_e32 v235, 0xffff0000, v235
	v_pk_fma_f32 v[122:123], v[122:123], v[218:219], v[212:213] op_sel_hi:[1,0,1]
	v_pk_mul_f32 v[232:233], v[218:219], v[232:233] op_sel:[1,0]
	v_pk_mul_f32 v[234:235], v[218:219], v[234:235] op_sel:[1,0]
	v_pk_fma_f32 v[106:107], v[106:107], v[218:219], v[232:233] op_sel_hi:[1,0,1]
	v_pk_fma_f32 v[108:109], v[108:109], v[218:219], v[234:235] op_sel_hi:[1,0,1]
	v_cvt_pk_bf16_f32 v232, v122, v123
	v_cvt_pk_bf16_f32 v233, v124, v125
	v_pk_fma_f32 v[122:123], v[122:123], v[122:123], 0 op_sel_hi:[1,1,0]
	v_pk_fma_f32 v[124:125], v[124:125], v[124:125], 0 op_sel_hi:[1,1,0]
	v_cvt_pk_bf16_f32 v234, v106, v107
	v_cvt_pk_bf16_f32 v235, v108, v109
	v_pk_fma_f32 v[106:107], v[106:107], v[106:107], v[122:123]
	v_pk_fma_f32 v[108:109], v[108:109], v[108:109], v[124:125]
	v_lshlrev_b32_e32 v122, 16, v236
	v_and_b32_e32 v123, 0xffff0000, v236
	v_lshlrev_b32_e32 v124, 16, v237
	v_and_b32_e32 v125, 0xffff0000, v237
	v_pk_mul_f32 v[122:123], v[218:219], v[122:123] op_sel:[1,0]
	v_pk_mul_f32 v[124:125], v[218:219], v[124:125] op_sel:[1,0]
	v_pk_fma_f32 v[70:71], v[70:71], v[218:219], v[122:123] op_sel_hi:[1,0,1]
	v_pk_fma_f32 v[72:73], v[72:73], v[218:219], v[124:125] op_sel_hi:[1,0,1]
	v_lshlrev_b32_e32 v122, 16, v238
	v_and_b32_e32 v123, 0xffff0000, v238
	v_lshlrev_b32_e32 v124, 16, v239
	v_and_b32_e32 v125, 0xffff0000, v239
	v_pk_mul_f32 v[122:123], v[218:219], v[122:123] op_sel:[1,0]
	v_pk_mul_f32 v[124:125], v[218:219], v[124:125] op_sel:[1,0]
	v_pk_fma_f32 v[46:47], v[46:47], v[218:219], v[122:123] op_sel_hi:[1,0,1]
	v_pk_fma_f32 v[48:49], v[48:49], v[218:219], v[124:125] op_sel_hi:[1,0,1]
	v_cvt_pk_bf16_f32 v122, v70, v71
	v_cvt_pk_bf16_f32 v123, v72, v73
	v_pk_fma_f32 v[70:71], v[70:71], v[70:71], v[106:107]
	v_pk_fma_f32 v[72:73], v[72:73], v[72:73], v[108:109]
	v_cvt_pk_bf16_f32 v124, v46, v47
	v_cvt_pk_bf16_f32 v125, v48, v49
	v_pk_fma_f32 v[46:47], v[46:47], v[46:47], v[70:71]
	v_pk_fma_f32 v[48:49], v[48:49], v[48:49], v[72:73]
	v_add_f32_e32 v46, v46, v47
	v_add_f32_e32 v47, v48, v49
	v_add_f32_e32 v46, v46, v47
	ds_bpermute_b32 v47, v192, v46
	v_lshl_add_u64 v[216:217], v[184:185], 0, s[34:35]
	v_mov_b32_dpp v70, v122 quad_perm:[1,0,3,2] row_mask:0xf bank_mask:0xf bound_ctrl:1
	v_mov_b32_dpp v71, v123 quad_perm:[1,0,3,2] row_mask:0xf bank_mask:0xf bound_ctrl:1
	v_mov_b32_dpp v72, v124 quad_perm:[1,0,3,2] row_mask:0xf bank_mask:0xf bound_ctrl:1
	s_waitcnt lgkmcnt(0)
	v_add_f32_e32 v46, v46, v47
	ds_bpermute_b32 v47, v193, v46
	v_mov_b32_dpp v73, v125 quad_perm:[1,0,3,2] row_mask:0xf bank_mask:0xf bound_ctrl:1
	v_lshl_add_u64 v[48:49], v[172:173], 1, v[216:217]
	v_mov_b32_dpp v106, v232 quad_perm:[1,0,3,2] row_mask:0xf bank_mask:0xf bound_ctrl:1
	v_mov_b32_dpp v107, v233 quad_perm:[1,0,3,2] row_mask:0xf bank_mask:0xf bound_ctrl:1
	v_mov_b32_dpp v108, v234 quad_perm:[1,0,3,2] row_mask:0xf bank_mask:0xf bound_ctrl:1
	v_mov_b32_dpp v109, v235 quad_perm:[1,0,3,2] row_mask:0xf bank_mask:0xf bound_ctrl:1
	v_cndmask_b32_e64 v70, v70, v232, s[4:5]
	v_cndmask_b32_e64 v71, v71, v233, s[4:5]
	v_cndmask_b32_e64 v72, v72, v234, s[4:5]
	v_cndmask_b32_e64 v73, v73, v235, s[4:5]
	v_lshl_add_u64 v[48:49], v[48:49], 0, v[170:171]
	v_cndmask_b32_e64 v106, v122, v106, s[4:5]
	v_cndmask_b32_e64 v107, v123, v107, s[4:5]
	v_cndmask_b32_e64 v108, v124, v108, s[4:5]
	v_cndmask_b32_e64 v109, v125, v109, s[4:5]
	global_store_dwordx4 v[48:49], v[70:73], off
	global_store_dwordx4 v[48:49], v[106:109], off offset:2048
	s_and_saveexec_b64 s[60:61], s[6:7]
	s_cbranch_execz .LBB0_759
	v_lshl_add_u64 v[48:49], s[12:13], 2, v[186:187]
	s_waitcnt lgkmcnt(0)
	v_add_f32_e32 v70, v46, v47
	v_add_co_u32_e32 v46, vcc, 0x2000, v48
	s_nop 1
	v_addc_co_u32_e32 v47, vcc, 0, v49, vcc
	global_store_dword v[46:47], v70, off offset:3072
